# P2: silu(z) gate loads use nt policy (read once); plus P0/P3 x loads nt
# speedup vs baseline: 1.0108x; 1.0108x over previous
.LBB0_265:
	s_cmpk_gt_u32 s36, 0xff
	s_waitcnt lgkmcnt(0)
	s_barrier
	s_cbranch_scc1 .LBB0_267
	ds_read2st64_b32 v[78:79], v64 offset1:1
	ds_read2st64_b32 v[80:81], v64 offset0:2 offset1:3
	ds_read2st64_b32 v[82:83], v64 offset0:4 offset1:5
	ds_read2st64_b32 v[84:85], v64 offset0:6 offset1:7
	ds_read2st64_b32 v[86:87], v64 offset0:8 offset1:9
	ds_read2st64_b32 v[126:127], v64 offset0:10 offset1:11
	ds_read2st64_b32 v[128:129], v64 offset0:12 offset1:13
	ds_read2st64_b32 v[132:133], v64 offset0:14 offset1:15
	ds_read2st64_b32 v[134:135], v64 offset0:16 offset1:17
	ds_read2st64_b32 v[136:137], v64 offset0:18 offset1:19
	ds_read2st64_b32 v[138:139], v64 offset0:20 offset1:21
	ds_read2st64_b32 v[140:141], v64 offset0:22 offset1:23
	ds_read2st64_b32 v[142:143], v64 offset0:24 offset1:25
	ds_read2st64_b32 v[144:145], v64 offset0:26 offset1:27
	ds_read2st64_b32 v[124:125], v64 offset0:28 offset1:29
	ds_read2st64_b32 v[146:147], v64 offset0:30 offset1:31
	ds_read2st64_b32 v[116:117], v64 offset0:32 offset1:33
	ds_read2st64_b32 v[120:121], v64 offset0:34 offset1:35
	ds_read2st64_b32 v[106:107], v64 offset0:36 offset1:37
	ds_read2st64_b32 v[114:115], v64 offset0:38 offset1:39
	ds_read2st64_b32 v[94:95], v64 offset0:40 offset1:41
	ds_read2st64_b32 v[100:101], v64 offset0:42 offset1:43
	ds_read2st64_b32 v[92:93], v64 offset0:44 offset1:45
	ds_read2st64_b32 v[96:97], v64 offset0:46 offset1:47
	ds_read2st64_b32 v[88:89], v64 offset0:56 offset1:57
	ds_read2st64_b32 v[90:91], v64 offset0:58 offset1:59
	ds_read2st64_b32 v[66:67], v64 offset0:60 offset1:61
	ds_read2st64_b32 v[68:69], v64 offset0:62 offset1:63
	ds_read2st64_b32 v[104:105], v64 offset0:48 offset1:49
	ds_read2st64_b32 v[110:111], v64 offset0:50 offset1:51
	ds_read2st64_b32 v[98:99], v64 offset0:52 offset1:53
	ds_read2st64_b32 v[102:103], v64 offset0:54 offset1:55
	s_waitcnt lgkmcnt(14)
	v_pk_mul_f32 v[78:79], v[180:181], v[78:79]
	v_pk_mul_f32 v[80:81], v[180:181], v[80:81]
	v_pk_fma_f32 v[48:49], v[48:49], v[70:71], v[78:79] op_sel_hi:[1,0,1] neg_lo:[0,0,1] neg_hi:[0,0,1]
	v_pk_mul_f32 v[78:79], v[180:181], v[84:85]
	v_pk_fma_f32 v[50:51], v[50:51], v[70:71], v[80:81] op_sel_hi:[1,0,1] neg_lo:[0,0,1] neg_hi:[0,0,1]
	v_pk_fma_f32 v[54:55], v[54:55], v[70:71], v[78:79] op_sel_hi:[1,0,1] neg_lo:[0,0,1] neg_hi:[0,0,1]
	v_pk_mul_f32 v[78:79], v[180:181], v[82:83]
	s_waitcnt lgkmcnt(5)
	v_pk_mul_f32 v[64:65], v[180:181], v[66:67]
	v_pk_fma_f32 v[78:79], v[52:53], v[70:71], v[78:79] op_sel_hi:[1,0,1] neg_lo:[0,0,1] neg_hi:[0,0,1]
	v_pk_mul_f32 v[52:53], v[180:181], v[126:127]
	v_pk_fma_f32 v[64:65], v[12:13], v[70:71], v[64:65] op_sel_hi:[1,0,1] neg_lo:[0,0,1] neg_hi:[0,0,1]
	v_pk_fma_f32 v[52:53], v[58:59], v[70:71], v[52:53] op_sel_hi:[1,0,1] neg_lo:[0,0,1] neg_hi:[0,0,1]
	v_pk_mul_f32 v[58:59], v[180:181], v[86:87]
	s_waitcnt lgkmcnt(4)
	v_pk_mul_f32 v[12:13], v[180:181], v[68:69]
	v_pk_fma_f32 v[80:81], v[56:57], v[70:71], v[58:59] op_sel_hi:[1,0,1] neg_lo:[0,0,1] neg_hi:[0,0,1]
	v_pk_mul_f32 v[56:57], v[180:181], v[132:133]
	v_pk_fma_f32 v[66:67], v[14:15], v[70:71], v[12:13] op_sel_hi:[1,0,1] neg_lo:[0,0,1] neg_hi:[0,0,1]
	v_pk_fma_f32 v[62:63], v[62:63], v[70:71], v[56:57] op_sel_hi:[1,0,1] neg_lo:[0,0,1] neg_hi:[0,0,1]
	v_pk_mul_f32 v[56:57], v[180:181], v[128:129]
	v_lshlrev_b32_e32 v12, 10, v159
	v_pk_fma_f32 v[84:85], v[60:61], v[70:71], v[56:57] op_sel_hi:[1,0,1] neg_lo:[0,0,1] neg_hi:[0,0,1]
	v_pk_mul_f32 v[56:57], v[180:181], v[136:137]
	v_lshl_or_b32 v12, s26, 7, v12
	v_pk_fma_f32 v[56:57], v[34:35], v[70:71], v[56:57] op_sel_hi:[1,0,1] neg_lo:[0,0,1] neg_hi:[0,0,1]
	v_pk_mul_f32 v[34:35], v[180:181], v[134:135]
	v_or_b32_e32 v68, s27, v12
	v_pk_fma_f32 v[60:61], v[32:33], v[70:71], v[34:35] op_sel_hi:[1,0,1] neg_lo:[0,0,1] neg_hi:[0,0,1]
	v_pk_mul_f32 v[32:33], v[180:181], v[140:141]
	v_lshlrev_b32_e32 v130, 1, v68
	v_pk_fma_f32 v[58:59], v[38:39], v[70:71], v[32:33] op_sel_hi:[1,0,1] neg_lo:[0,0,1] neg_hi:[0,0,1]
	v_pk_mul_f32 v[32:33], v[180:181], v[138:139]
	v_lshl_add_u64 v[68:69], s[16:17], 0, v[130:131]
	v_pk_fma_f32 v[82:83], v[36:37], v[70:71], v[32:33] op_sel_hi:[1,0,1] neg_lo:[0,0,1] neg_hi:[0,0,1]
	v_pk_mul_f32 v[32:33], v[180:181], v[144:145]
	v_mov_b32_e32 v159, v131
	v_pk_fma_f32 v[42:43], v[42:43], v[70:71], v[32:33] op_sel_hi:[1,0,1] neg_lo:[0,0,1] neg_hi:[0,0,1]
	v_pk_mul_f32 v[32:33], v[180:181], v[142:143]
	v_pk_mul_f32 v[112:113], v[48:49], v[48:49]
	v_pk_fma_f32 v[86:87], v[40:41], v[70:71], v[32:33] op_sel_hi:[1,0,1] neg_lo:[0,0,1] neg_hi:[0,0,1]
	v_pk_mul_f32 v[32:33], v[180:181], v[146:147]
	global_load_dwordx4 v[12:15], v156, s[40:41]
	v_pk_fma_f32 v[40:41], v[46:47], v[70:71], v[32:33] op_sel_hi:[1,0,1] neg_lo:[0,0,1] neg_hi:[0,0,1]
	v_pk_mul_f32 v[32:33], v[180:181], v[124:125]
	v_lshl_add_u64 v[68:69], v[68:69], 0, v[158:159]
	v_pk_fma_f32 v[44:45], v[44:45], v[70:71], v[32:33] op_sel_hi:[1,0,1] neg_lo:[0,0,1] neg_hi:[0,0,1]
	v_pk_mul_f32 v[32:33], v[180:181], v[120:121]
	v_pk_mul_f32 v[108:109], v[50:51], v[50:51]
	v_pk_fma_f32 v[32:33], v[18:19], v[70:71], v[32:33] op_sel_hi:[1,0,1] neg_lo:[0,0,1] neg_hi:[0,0,1]
	v_pk_mul_f32 v[18:19], v[180:181], v[116:117]
	global_load_dwordx2 v[74:75], v[68:69], off nt
	v_pk_fma_f32 v[34:35], v[16:17], v[70:71], v[18:19] op_sel_hi:[1,0,1] neg_lo:[0,0,1] neg_hi:[0,0,1]
	v_pk_mul_f32 v[16:17], v[180:181], v[114:115]
	v_pk_mul_f32 v[122:123], v[78:79], v[78:79]
	v_pk_fma_f32 v[36:37], v[22:23], v[70:71], v[16:17] op_sel_hi:[1,0,1] neg_lo:[0,0,1] neg_hi:[0,0,1]
	v_pk_mul_f32 v[16:17], v[180:181], v[106:107]
	v_pk_mul_f32 v[118:119], v[54:55], v[54:55]
	v_pk_fma_f32 v[38:39], v[20:21], v[70:71], v[16:17] op_sel_hi:[1,0,1] neg_lo:[0,0,1] neg_hi:[0,0,1]
	v_pk_mul_f32 v[16:17], v[180:181], v[100:101]
	v_pk_mul_f32 v[148:149], v[80:81], v[80:81]
	v_pk_fma_f32 v[26:27], v[26:27], v[70:71], v[16:17] op_sel_hi:[1,0,1] neg_lo:[0,0,1] neg_hi:[0,0,1]
	v_pk_mul_f32 v[16:17], v[180:181], v[94:95]
	v_pk_mul_f32 v[126:127], v[52:53], v[52:53]
	v_pk_fma_f32 v[24:25], v[24:25], v[70:71], v[16:17] op_sel_hi:[1,0,1] neg_lo:[0,0,1] neg_hi:[0,0,1]
	v_pk_mul_f32 v[16:17], v[180:181], v[96:97]
	v_pk_mul_f32 v[128:129], v[84:85], v[84:85]
	v_pk_fma_f32 v[20:21], v[30:31], v[70:71], v[16:17] op_sel_hi:[1,0,1] neg_lo:[0,0,1] neg_hi:[0,0,1]
	v_pk_mul_f32 v[16:17], v[180:181], v[92:93]
	v_pk_mul_f32 v[132:133], v[62:63], v[62:63]
	v_pk_fma_f32 v[22:23], v[28:29], v[70:71], v[16:17] op_sel_hi:[1,0,1] neg_lo:[0,0,1] neg_hi:[0,0,1]
	s_waitcnt lgkmcnt(2)
	v_pk_mul_f32 v[16:17], v[180:181], v[110:111]
	v_pk_mul_f32 v[134:135], v[60:61], v[60:61]
	v_pk_fma_f32 v[16:17], v[2:3], v[70:71], v[16:17] op_sel_hi:[1,0,1] neg_lo:[0,0,1] neg_hi:[0,0,1]
	v_pk_mul_f32 v[2:3], v[180:181], v[104:105]
	v_pk_mul_f32 v[136:137], v[56:57], v[56:57]
	v_pk_fma_f32 v[18:19], v[0:1], v[70:71], v[2:3] op_sel_hi:[1,0,1] neg_lo:[0,0,1] neg_hi:[0,0,1]
	s_waitcnt lgkmcnt(0)
	v_pk_mul_f32 v[0:1], v[180:181], v[102:103]
	v_pk_mul_f32 v[2:3], v[180:181], v[98:99]
	v_pk_fma_f32 v[0:1], v[6:7], v[70:71], v[0:1] op_sel_hi:[1,0,1] neg_lo:[0,0,1] neg_hi:[0,0,1]
	v_pk_fma_f32 v[4:5], v[4:5], v[70:71], v[2:3] op_sel_hi:[1,0,1] neg_lo:[0,0,1] neg_hi:[0,0,1]
	v_pk_mul_f32 v[2:3], v[180:181], v[90:91]
	v_pk_mul_f32 v[6:7], v[180:181], v[88:89]
	v_pk_fma_f32 v[2:3], v[10:11], v[70:71], v[2:3] op_sel_hi:[1,0,1] neg_lo:[0,0,1] neg_hi:[0,0,1]
	v_pk_fma_f32 v[6:7], v[8:9], v[70:71], v[6:7] op_sel_hi:[1,0,1] neg_lo:[0,0,1] neg_hi:[0,0,1]
	v_add_f32_e32 v70, v112, v113
	v_add_f32_e32 v70, v70, v108
	v_add_f32_e32 v70, v70, v109
	v_add_f32_e32 v70, v70, v122
	v_add_f32_e32 v70, v70, v123
	v_add_f32_e32 v70, v70, v118
	v_add_f32_e32 v70, v70, v119
	v_add_f32_e32 v70, v70, v148
	v_add_f32_e32 v70, v70, v149
	v_add_f32_e32 v70, v70, v126
	v_add_f32_e32 v70, v70, v127
	v_add_f32_e32 v70, v70, v128
	v_add_f32_e32 v70, v70, v129
	v_add_f32_e32 v70, v70, v132
	v_add_f32_e32 v70, v70, v133
	v_add_f32_e32 v70, v70, v134
	v_add_f32_e32 v70, v70, v135
	v_add_f32_e32 v70, v70, v136
	v_pk_mul_f32 v[138:139], v[82:83], v[82:83]
	v_add_f32_e32 v70, v70, v137
	v_add_f32_e32 v70, v70, v138
	v_pk_mul_f32 v[140:141], v[58:59], v[58:59]
	v_add_f32_e32 v70, v70, v139
	v_add_f32_e32 v70, v70, v140
	v_pk_mul_f32 v[142:143], v[86:87], v[86:87]
	v_add_f32_e32 v70, v70, v141
	v_add_f32_e32 v70, v70, v142
	v_pk_mul_f32 v[144:145], v[42:43], v[42:43]
	v_add_f32_e32 v70, v70, v143
	v_add_f32_e32 v70, v70, v144
	v_pk_mul_f32 v[124:125], v[44:45], v[44:45]
	v_add_f32_e32 v70, v70, v145
	v_add_f32_e32 v70, v70, v124
	v_pk_mul_f32 v[46:47], v[40:41], v[40:41]
	v_add_f32_e32 v70, v70, v125
	v_add_f32_e32 v46, v70, v46
	v_pk_mul_f32 v[116:117], v[34:35], v[34:35]
	v_add_f32_e32 v46, v46, v47
	v_add_f32_e32 v46, v46, v116
	v_pk_mul_f32 v[120:121], v[32:33], v[32:33]
	v_add_f32_e32 v46, v46, v117
	v_add_f32_e32 v46, v46, v120
	v_pk_mul_f32 v[106:107], v[38:39], v[38:39]
	v_add_f32_e32 v46, v46, v121
	v_add_f32_e32 v46, v46, v106
	v_pk_mul_f32 v[114:115], v[36:37], v[36:37]
	v_add_f32_e32 v46, v46, v107
	v_add_f32_e32 v46, v46, v114
	v_pk_mul_f32 v[94:95], v[24:25], v[24:25]
	v_add_f32_e32 v46, v46, v115
	v_add_f32_e32 v46, v46, v94
	v_pk_mul_f32 v[100:101], v[26:27], v[26:27]
	v_add_f32_e32 v46, v46, v95
	v_add_f32_e32 v46, v46, v100
	v_pk_mul_f32 v[28:29], v[22:23], v[22:23]
	v_add_f32_e32 v46, v46, v101
	v_add_f32_e32 v28, v46, v28
	v_pk_mul_f32 v[30:31], v[20:21], v[20:21]
	v_add_f32_e32 v28, v28, v29
	v_add_f32_e32 v28, v28, v30
	v_pk_mul_f32 v[96:97], v[18:19], v[18:19]
	v_add_f32_e32 v28, v28, v31
	v_add_f32_e32 v28, v28, v96
	v_pk_mul_f32 v[92:93], v[16:17], v[16:17]
	v_add_f32_e32 v28, v28, v97
	v_add_f32_e32 v28, v28, v92
	v_pk_mul_f32 v[98:99], v[4:5], v[4:5]
	v_add_f32_e32 v28, v28, v93
	v_add_f32_e32 v28, v28, v98
	v_pk_mul_f32 v[102:103], v[0:1], v[0:1]
	v_add_f32_e32 v28, v28, v99
	v_add_f32_e32 v28, v28, v102
	v_pk_mul_f32 v[8:9], v[6:7], v[6:7]
	v_add_f32_e32 v28, v28, v103
	v_add_f32_e32 v8, v28, v8
	v_pk_mul_f32 v[10:11], v[2:3], v[2:3]
	v_add_f32_e32 v8, v8, v9
	v_add_f32_e32 v8, v8, v10
	v_pk_mul_f32 v[72:73], v[64:65], v[64:65]
	v_add_f32_e32 v8, v8, v11
	v_add_f32_e32 v8, v8, v72
	v_pk_mul_f32 v[76:77], v[66:67], v[66:67]
	v_add_f32_e32 v8, v8, v73
	v_add_f32_e32 v8, v8, v76
	v_add_f32_e32 v8, v8, v77
	ds_bpermute_b32 v9, v194, v8
	s_waitcnt vmcnt(0)
	v_lshlrev_b32_e32 v70, 16, v74
	v_and_b32_e32 v71, 0xffff0000, v74
	v_lshlrev_b32_e32 v72, 16, v75
	v_and_b32_e32 v73, 0xffff0000, v75
	s_waitcnt lgkmcnt(0)
	v_add_f32_e32 v8, v8, v9
	v_fmamk_f32 v8, v8, 0x3c000000, v195
	v_mul_f32_e32 v9, 0x4b800000, v8
	v_cmp_gt_f32_e32 vcc, s65, v8
	global_load_dwordx2 v[28:29], v[68:69], off offset:16 nt
	global_load_dwordx2 v[30:31], v[68:69], off offset:32 nt
	global_load_dwordx2 v[46:47], v[68:69], off offset:48 nt
	v_cndmask_b32_e32 v8, v8, v9, vcc
	v_rsq_f32_e32 v10, v8
	v_lshl_add_u64 v[8:9], s[18:19], 0, v[130:131]
	v_lshl_add_u64 v[8:9], v[8:9], 0, v[158:159]
	v_mul_f32_e32 v11, 0x45800000, v10
	v_cndmask_b32_e32 v10, v10, v11, vcc
	v_mul_f32_e32 v10, 0x3f4ccccd, v10
	v_pk_mul_f32 v[48:49], v[48:49], v[10:11] op_sel_hi:[1,0]
	v_pk_mul_f32 v[42:43], v[42:43], v[10:11] op_sel_hi:[1,0]
	v_pk_mul_f32 v[12:13], v[12:13], v[48:49]
	v_pk_mul_f32 v[48:49], v[50:51], v[10:11] op_sel_hi:[1,0]
	v_pk_mul_f32 v[12:13], v[12:13], v[70:71]
	v_pk_mul_f32 v[14:15], v[14:15], v[48:49]
	v_cvt_pk_bf16_f32 v12, v12, v13
	v_pk_mul_f32 v[14:15], v[14:15], v[72:73]
	v_pk_mul_f32 v[50:51], v[78:79], v[10:11] op_sel_hi:[1,0]
	v_cvt_pk_bf16_f32 v13, v14, v15
	global_store_dwordx2 v[8:9], v[12:13], off
	global_load_dwordx4 v[12:15], v156, s[40:41] offset:32
	v_pk_mul_f32 v[44:45], v[44:45], v[10:11] op_sel_hi:[1,0]
	v_pk_mul_f32 v[40:41], v[40:41], v[10:11] op_sel_hi:[1,0]
	v_pk_mul_f32 v[34:35], v[34:35], v[10:11] op_sel_hi:[1,0]
	v_pk_mul_f32 v[32:33], v[32:33], v[10:11] op_sel_hi:[1,0]
	v_pk_mul_f32 v[24:25], v[24:25], v[10:11] op_sel_hi:[1,0]
	v_pk_mul_f32 v[26:27], v[26:27], v[10:11] op_sel_hi:[1,0]
	v_pk_mul_f32 v[22:23], v[22:23], v[10:11] op_sel_hi:[1,0]
	v_pk_mul_f32 v[20:21], v[20:21], v[10:11] op_sel_hi:[1,0]
	v_pk_mul_f32 v[18:19], v[18:19], v[10:11] op_sel_hi:[1,0]
	v_pk_mul_f32 v[16:17], v[16:17], v[10:11] op_sel_hi:[1,0]
	v_pk_mul_f32 v[4:5], v[4:5], v[10:11] op_sel_hi:[1,0]
	v_pk_mul_f32 v[0:1], v[0:1], v[10:11] op_sel_hi:[1,0]
	v_pk_mul_f32 v[6:7], v[6:7], v[10:11] op_sel_hi:[1,0]
	v_pk_mul_f32 v[2:3], v[2:3], v[10:11] op_sel_hi:[1,0]
	s_waitcnt vmcnt(4)
	v_lshlrev_b32_e32 v48, 16, v28
	v_and_b32_e32 v49, 0xffff0000, v28
	v_lshlrev_b32_e32 v28, 16, v29
	v_and_b32_e32 v29, 0xffff0000, v29
	s_waitcnt vmcnt(0)
	v_pk_mul_f32 v[12:13], v[12:13], v[50:51]
	s_nop 0
	v_pk_mul_f32 v[12:13], v[12:13], v[48:49]
	v_pk_mul_f32 v[48:49], v[54:55], v[10:11] op_sel_hi:[1,0]
	v_cvt_pk_bf16_f32 v12, v12, v13
	v_pk_mul_f32 v[14:15], v[14:15], v[48:49]
	v_pk_mul_f32 v[48:49], v[80:81], v[10:11] op_sel_hi:[1,0]
	v_pk_mul_f32 v[14:15], v[14:15], v[28:29]
	v_pk_mul_f32 v[50:51], v[52:53], v[10:11] op_sel_hi:[1,0]
	v_cvt_pk_bf16_f32 v13, v14, v15
	global_store_dwordx2 v[8:9], v[12:13], off offset:16
	global_load_dwordx4 v[12:15], v156, s[40:41] offset:64
	v_lshlrev_b32_e32 v28, 16, v30
	v_and_b32_e32 v29, 0xffff0000, v30
	v_lshlrev_b32_e32 v30, 16, v31
	v_and_b32_e32 v31, 0xffff0000, v31
	v_pk_mul_f32 v[52:53], v[60:61], v[10:11] op_sel_hi:[1,0]
	v_pk_mul_f32 v[54:55], v[56:57], v[10:11] op_sel_hi:[1,0]
	s_waitcnt vmcnt(0)
	v_pk_mul_f32 v[12:13], v[48:49], v[12:13]
	v_pk_mul_f32 v[14:15], v[50:51], v[14:15]
	v_pk_mul_f32 v[12:13], v[12:13], v[28:29]
	v_pk_mul_f32 v[14:15], v[14:15], v[30:31]
	v_cvt_pk_bf16_f32 v12, v12, v13
	v_cvt_pk_bf16_f32 v13, v14, v15
	global_store_dwordx2 v[8:9], v[12:13], off offset:32
	global_load_dwordx4 v[12:15], v156, s[40:41] offset:96
	s_nop 0
	global_load_dwordx2 v[28:29], v[68:69], off offset:64 nt
	v_pk_mul_f32 v[48:49], v[84:85], v[10:11] op_sel_hi:[1,0]
	v_pk_mul_f32 v[50:51], v[62:63], v[10:11] op_sel_hi:[1,0]
	v_lshlrev_b32_e32 v30, 16, v46
	v_and_b32_e32 v31, 0xffff0000, v46
	v_lshlrev_b32_e32 v46, 16, v47
	v_and_b32_e32 v47, 0xffff0000, v47
	s_waitcnt vmcnt(1)
	v_pk_mul_f32 v[12:13], v[48:49], v[12:13]
	v_pk_mul_f32 v[14:15], v[50:51], v[14:15]
	v_pk_mul_f32 v[12:13], v[12:13], v[30:31]
	v_pk_mul_f32 v[14:15], v[14:15], v[46:47]
	v_cvt_pk_bf16_f32 v12, v12, v13
	v_cvt_pk_bf16_f32 v13, v14, v15
	global_store_dwordx2 v[8:9], v[12:13], off offset:48
	global_load_dwordx4 v[12:15], v156, s[40:41] offset:128
	s_nop 0
	global_load_dwordx2 v[30:31], v[68:69], off offset:80 nt
	global_load_dwordx2 v[46:47], v[68:69], off offset:96 nt
	global_load_dwordx2 v[48:49], v[68:69], off offset:112 nt
	s_waitcnt vmcnt(5)
	v_lshlrev_b32_e32 v50, 16, v28
	v_and_b32_e32 v51, 0xffff0000, v28
	v_lshlrev_b32_e32 v28, 16, v29
	v_and_b32_e32 v29, 0xffff0000, v29
	s_waitcnt vmcnt(3)
	v_pk_mul_f32 v[12:13], v[52:53], v[12:13]
	v_pk_mul_f32 v[14:15], v[54:55], v[14:15]
	v_pk_mul_f32 v[12:13], v[12:13], v[50:51]
	v_pk_mul_f32 v[14:15], v[14:15], v[28:29]
	v_cvt_pk_bf16_f32 v12, v12, v13
	v_cvt_pk_bf16_f32 v13, v14, v15
	global_store_dwordx2 v[8:9], v[12:13], off offset:64
	global_load_dwordx4 v[12:15], v156, s[40:41] offset:160
	v_pk_mul_f32 v[50:51], v[82:83], v[10:11] op_sel_hi:[1,0]
	v_pk_mul_f32 v[52:53], v[58:59], v[10:11] op_sel_hi:[1,0]
	s_waitcnt vmcnt(4)
	v_lshlrev_b32_e32 v28, 16, v30
	v_and_b32_e32 v29, 0xffff0000, v30
	v_lshlrev_b32_e32 v30, 16, v31
	v_and_b32_e32 v31, 0xffff0000, v31
	s_waitcnt vmcnt(0)
	v_pk_mul_f32 v[12:13], v[50:51], v[12:13]
	v_pk_mul_f32 v[14:15], v[52:53], v[14:15]
	v_pk_mul_f32 v[12:13], v[12:13], v[28:29]
	v_pk_mul_f32 v[14:15], v[14:15], v[30:31]
	v_cvt_pk_bf16_f32 v12, v12, v13
	v_cvt_pk_bf16_f32 v13, v14, v15
	global_store_dwordx2 v[8:9], v[12:13], off offset:80
	global_load_dwordx4 v[12:15], v156, s[40:41] offset:192
	v_lshlrev_b32_e32 v28, 16, v46
	v_and_b32_e32 v29, 0xffff0000, v46
	v_lshlrev_b32_e32 v30, 16, v47
	v_and_b32_e32 v31, 0xffff0000, v47
	v_pk_mul_f32 v[46:47], v[86:87], v[10:11] op_sel_hi:[1,0]
	s_waitcnt vmcnt(0)
	v_pk_mul_f32 v[14:15], v[42:43], v[14:15]
	v_pk_mul_f32 v[12:13], v[46:47], v[12:13]
	v_pk_mul_f32 v[14:15], v[14:15], v[30:31]
	v_pk_mul_f32 v[12:13], v[12:13], v[28:29]
	v_lshlrev_b32_e32 v30, 16, v48
	v_cvt_pk_bf16_f32 v12, v12, v13
	v_cvt_pk_bf16_f32 v13, v14, v15
	global_store_dwordx2 v[8:9], v[12:13], off offset:96
	global_load_dwordx4 v[12:15], v156, s[40:41] offset:224
	s_nop 0
	global_load_dwordx2 v[28:29], v[68:69], off offset:128 nt
	v_and_b32_e32 v31, 0xffff0000, v48
	v_lshlrev_b32_e32 v42, 16, v49
	v_and_b32_e32 v43, 0xffff0000, v49
	s_waitcnt vmcnt(1)
	v_pk_mul_f32 v[12:13], v[44:45], v[12:13]
	v_pk_mul_f32 v[14:15], v[40:41], v[14:15]
	v_pk_mul_f32 v[12:13], v[12:13], v[30:31]
	v_pk_mul_f32 v[14:15], v[14:15], v[42:43]
	v_cvt_pk_bf16_f32 v12, v12, v13
	v_cvt_pk_bf16_f32 v13, v14, v15
	global_store_dwordx2 v[8:9], v[12:13], off offset:112
	global_load_dwordx4 v[12:15], v156, s[40:41] offset:256
	s_nop 0
	global_load_dwordx2 v[30:31], v[68:69], off offset:144 nt
	global_load_dwordx2 v[40:41], v[68:69], off offset:160 nt
	global_load_dwordx2 v[42:43], v[68:69], off offset:176 nt
	s_waitcnt vmcnt(5)
	v_lshlrev_b32_e32 v44, 16, v28
	v_and_b32_e32 v45, 0xffff0000, v28
	v_lshlrev_b32_e32 v28, 16, v29
	v_and_b32_e32 v29, 0xffff0000, v29
	s_waitcnt vmcnt(3)
	v_pk_mul_f32 v[12:13], v[34:35], v[12:13]
	v_pk_mul_f32 v[14:15], v[32:33], v[14:15]
	v_pk_mul_f32 v[12:13], v[12:13], v[44:45]
	v_pk_mul_f32 v[14:15], v[14:15], v[28:29]
	v_cvt_pk_bf16_f32 v12, v12, v13
	v_cvt_pk_bf16_f32 v13, v14, v15
	global_store_dwordx2 v[8:9], v[12:13], off offset:128
	global_load_dwordx4 v[12:15], v156, s[40:41] offset:288
	v_pk_mul_f32 v[32:33], v[38:39], v[10:11] op_sel_hi:[1,0]
	v_pk_mul_f32 v[34:35], v[36:37], v[10:11] op_sel_hi:[1,0]
	s_waitcnt vmcnt(4)
	v_lshlrev_b32_e32 v28, 16, v30
	v_and_b32_e32 v29, 0xffff0000, v30
	v_lshlrev_b32_e32 v30, 16, v31
	v_and_b32_e32 v31, 0xffff0000, v31
	s_waitcnt vmcnt(0)
	v_pk_mul_f32 v[12:13], v[32:33], v[12:13]
	v_pk_mul_f32 v[14:15], v[34:35], v[14:15]
	v_pk_mul_f32 v[12:13], v[12:13], v[28:29]
	v_pk_mul_f32 v[14:15], v[14:15], v[30:31]
	v_cvt_pk_bf16_f32 v12, v12, v13
	v_cvt_pk_bf16_f32 v13, v14, v15
	global_store_dwordx2 v[8:9], v[12:13], off offset:144
	global_load_dwordx4 v[12:15], v156, s[40:41] offset:320
	v_lshlrev_b32_e32 v28, 16, v40
	v_and_b32_e32 v29, 0xffff0000, v40
	v_lshlrev_b32_e32 v30, 16, v41
	v_and_b32_e32 v31, 0xffff0000, v41
	s_waitcnt vmcnt(0)
	v_pk_mul_f32 v[12:13], v[24:25], v[12:13]
	v_pk_mul_f32 v[14:15], v[26:27], v[14:15]
	v_pk_mul_f32 v[12:13], v[12:13], v[28:29]
	v_pk_mul_f32 v[14:15], v[14:15], v[30:31]
	v_cvt_pk_bf16_f32 v12, v12, v13
	v_cvt_pk_bf16_f32 v13, v14, v15
	global_store_dwordx2 v[8:9], v[12:13], off offset:160
	global_load_dwordx4 v[12:15], v156, s[40:41] offset:352
	s_nop 0
	global_load_dwordx2 v[24:25], v[68:69], off offset:192 nt
	v_lshlrev_b32_e32 v26, 16, v42
	v_and_b32_e32 v27, 0xffff0000, v42
	v_lshlrev_b32_e32 v28, 16, v43
	v_and_b32_e32 v29, 0xffff0000, v43
	s_waitcnt vmcnt(1)
	v_pk_mul_f32 v[12:13], v[22:23], v[12:13]
	v_pk_mul_f32 v[14:15], v[20:21], v[14:15]
	v_pk_mul_f32 v[12:13], v[12:13], v[26:27]
	v_pk_mul_f32 v[14:15], v[14:15], v[28:29]
	v_cvt_pk_bf16_f32 v12, v12, v13
	v_cvt_pk_bf16_f32 v13, v14, v15
	global_store_dwordx2 v[8:9], v[12:13], off offset:176
	global_load_dwordx4 v[12:15], v156, s[40:41] offset:384
	s_nop 0
	global_load_dwordx2 v[20:21], v[68:69], off offset:208 nt
	global_load_dwordx2 v[22:23], v[68:69], off offset:224 nt
	global_load_dwordx2 v[26:27], v[68:69], off offset:240 nt
	s_waitcnt vmcnt(5)
	v_lshlrev_b32_e32 v28, 16, v24
	v_and_b32_e32 v29, 0xffff0000, v24
	v_lshlrev_b32_e32 v24, 16, v25
	v_and_b32_e32 v25, 0xffff0000, v25
	s_waitcnt vmcnt(3)
	v_pk_mul_f32 v[12:13], v[18:19], v[12:13]
	v_pk_mul_f32 v[14:15], v[16:17], v[14:15]
	v_pk_mul_f32 v[12:13], v[12:13], v[28:29]
	v_pk_mul_f32 v[14:15], v[14:15], v[24:25]
	v_cvt_pk_bf16_f32 v12, v12, v13
	v_cvt_pk_bf16_f32 v13, v14, v15
	global_store_dwordx2 v[8:9], v[12:13], off offset:192
	global_load_dwordx4 v[12:15], v156, s[40:41] offset:416
	s_waitcnt vmcnt(4)
	v_lshlrev_b32_e32 v16, 16, v20
	v_and_b32_e32 v17, 0xffff0000, v20
	v_lshlrev_b32_e32 v18, 16, v21
	v_and_b32_e32 v19, 0xffff0000, v21
	s_waitcnt vmcnt(0)
	v_pk_mul_f32 v[4:5], v[4:5], v[12:13]
	v_pk_mul_f32 v[0:1], v[0:1], v[14:15]
	v_pk_mul_f32 v[4:5], v[4:5], v[16:17]
	v_pk_mul_f32 v[0:1], v[0:1], v[18:19]
	v_cvt_pk_bf16_f32 v4, v4, v5
	v_cvt_pk_bf16_f32 v5, v0, v1
	global_store_dwordx2 v[8:9], v[4:5], off offset:208
	global_load_dwordx4 v[12:15], v156, s[40:41] offset:448
	v_lshlrev_b32_e32 v0, 16, v22
	v_and_b32_e32 v1, 0xffff0000, v22
	v_lshlrev_b32_e32 v4, 16, v23
	v_and_b32_e32 v5, 0xffff0000, v23
	s_waitcnt vmcnt(0)
	v_pk_mul_f32 v[6:7], v[6:7], v[12:13]
	v_pk_mul_f32 v[2:3], v[2:3], v[14:15]
	v_pk_mul_f32 v[0:1], v[6:7], v[0:1]
	v_pk_mul_f32 v[2:3], v[2:3], v[4:5]
	v_cvt_pk_bf16_f32 v0, v0, v1
	v_cvt_pk_bf16_f32 v1, v2, v3
	global_store_dwordx2 v[8:9], v[0:1], off offset:224
	global_load_dwordx4 v[0:3], v156, s[40:41] offset:480
	v_pk_mul_f32 v[12:13], v[64:65], v[10:11] op_sel_hi:[1,0]
	v_pk_mul_f32 v[10:11], v[66:67], v[10:11] op_sel_hi:[1,0]
	v_lshlrev_b32_e32 v4, 16, v26
	v_and_b32_e32 v5, 0xffff0000, v26
	v_lshlrev_b32_e32 v6, 16, v27
	v_and_b32_e32 v7, 0xffff0000, v27
	s_waitcnt vmcnt(0)
	v_pk_mul_f32 v[0:1], v[12:13], v[0:1]
	v_pk_mul_f32 v[2:3], v[10:11], v[2:3]
	v_pk_mul_f32 v[0:1], v[0:1], v[4:5]
	v_pk_mul_f32 v[2:3], v[2:3], v[6:7]
	v_cvt_pk_bf16_f32 v0, v0, v1
	v_cvt_pk_bf16_f32 v1, v2, v3
	global_store_dwordx2 v[8:9], v[0:1], off offset:240

.LBB0_285:
	v_lshl_add_u64 v[74:75], v[190:191], 0, s[20:21]
	v_lshlrev_b64 v[74:75], 10, v[74:75]
	v_lshl_add_u64 v[74:75], v[74:75], 0, s[22:23]
	v_lshlrev_b64 v[74:75], 1, v[74:75]
	v_lshl_add_u64 v[76:77], v[186:187], 0, v[74:75]
	global_load_dwordx2 v[78:79], v[76:77], off nt
	global_load_dwordx2 v[80:81], v[76:77], off offset:16 nt
	global_load_dwordx2 v[82:83], v[76:77], off offset:32 nt
	global_load_dwordx2 v[84:85], v[76:77], off offset:48 nt
	global_load_dwordx2 v[86:87], v[76:77], off offset:64 nt
	global_load_dwordx2 v[88:89], v[76:77], off offset:80 nt
	global_load_dwordx2 v[90:91], v[76:77], off offset:96 nt
	v_div_scale_f32 v92, s[26:27], v70, v70, 1.0
	global_load_dwordx2 v[76:77], v[76:77], off offset:112 nt
	v_rcp_f32_e32 v93, v92
	v_div_scale_f32 v94, vcc, 1.0, v70, 1.0
	v_lshl_add_u64 v[74:75], v[188:189], 0, v[74:75]
	v_fma_f32 v95, -v92, v93, 1.0
	v_fmac_f32_e32 v93, v95, v93
	v_mul_f32_e32 v95, v94, v93
	v_fma_f32 v96, -v92, v95, v94
	v_fmac_f32_e32 v95, v96, v93
	v_fma_f32 v92, -v92, v95, v94
	v_div_fmas_f32 v92, v92, v93, v95
	v_div_fixup_f32 v92, v92, v70, 1.0
	v_pk_mul_f32 v[94:95], v[48:49], v[92:93] op_sel_hi:[1,0]
	v_pk_mul_f32 v[96:97], v[50:51], v[92:93] op_sel_hi:[1,0]
	v_pk_mul_f32 v[98:99], v[52:53], v[92:93] op_sel_hi:[1,0]
	v_pk_mul_f32 v[100:101], v[54:55], v[92:93] op_sel_hi:[1,0]
	v_pk_mul_f32 v[102:103], v[56:57], v[92:93] op_sel_hi:[1,0]
	s_waitcnt vmcnt(9)
	v_pk_mul_f32 v[104:105], v[58:59], v[92:93] op_sel_hi:[1,0]
	v_pk_mul_f32 v[106:107], v[60:61], v[92:93] op_sel_hi:[1,0]
	s_waitcnt vmcnt(8)
	v_pk_mul_f32 v[108:109], v[62:63], v[92:93] op_sel_hi:[1,0]
	v_pk_mul_f32 v[110:111], v[32:33], v[92:93] op_sel_hi:[1,0]
	v_pk_mul_f32 v[112:113], v[34:35], v[92:93] op_sel_hi:[1,0]
	v_pk_mul_f32 v[116:117], v[38:39], v[92:93] op_sel_hi:[1,0]
	v_pk_mul_f32 v[114:115], v[36:37], v[92:93] op_sel_hi:[1,0]
	s_waitcnt vmcnt(7)
	v_lshlrev_b32_e32 v118, 16, v78
	v_and_b32_e32 v119, 0xffff0000, v78
	v_lshlrev_b32_e32 v78, 16, v79
	v_and_b32_e32 v79, 0xffff0000, v79
	s_waitcnt vmcnt(6)
	v_lshlrev_b32_e32 v120, 16, v80
	v_and_b32_e32 v121, 0xffff0000, v80
	v_lshlrev_b32_e32 v80, 16, v81
	v_and_b32_e32 v81, 0xffff0000, v81
	s_waitcnt vmcnt(5)
	v_lshlrev_b32_e32 v122, 16, v82
	v_and_b32_e32 v123, 0xffff0000, v82
	v_lshlrev_b32_e32 v82, 16, v83
	v_and_b32_e32 v83, 0xffff0000, v83
	s_waitcnt vmcnt(4)
	v_lshlrev_b32_e32 v124, 16, v84
	v_and_b32_e32 v125, 0xffff0000, v84
	v_lshlrev_b32_e32 v84, 16, v85
	v_and_b32_e32 v85, 0xffff0000, v85
	s_waitcnt vmcnt(3)
	v_lshlrev_b32_e32 v126, 16, v86
	v_and_b32_e32 v127, 0xffff0000, v86
	v_lshlrev_b32_e32 v86, 16, v87
	v_and_b32_e32 v87, 0xffff0000, v87
	v_pk_mul_f32 v[94:95], v[94:95], v[118:119]
	v_pk_mul_f32 v[78:79], v[96:97], v[78:79]
	v_pk_mul_f32 v[96:97], v[98:99], v[120:121]
	v_pk_mul_f32 v[80:81], v[100:101], v[80:81]
	v_pk_mul_f32 v[98:99], v[102:103], v[122:123]
	v_pk_mul_f32 v[82:83], v[104:105], v[82:83]
	v_pk_mul_f32 v[100:101], v[106:107], v[124:125]
	v_pk_mul_f32 v[84:85], v[108:109], v[84:85]
	v_pk_mul_f32 v[102:103], v[110:111], v[126:127]
	v_pk_mul_f32 v[86:87], v[112:113], v[86:87]
	v_cvt_pk_bf16_f32 v94, v94, v95
	v_cvt_pk_bf16_f32 v95, v78, v79
	v_cvt_pk_bf16_f32 v78, v96, v97
	v_cvt_pk_bf16_f32 v79, v80, v81
	v_cvt_pk_bf16_f32 v80, v98, v99
	v_cvt_pk_bf16_f32 v81, v82, v83
	v_cvt_pk_bf16_f32 v82, v100, v101
	v_cvt_pk_bf16_f32 v83, v84, v85
	v_cvt_pk_bf16_f32 v84, v102, v103
	v_cvt_pk_bf16_f32 v85, v86, v87
	global_store_dwordx2 v[74:75], v[94:95], off
	global_store_dwordx2 v[74:75], v[78:79], off offset:16
	global_store_dwordx2 v[74:75], v[80:81], off offset:32
	global_store_dwordx2 v[74:75], v[82:83], off offset:48
	global_store_dwordx2 v[74:75], v[84:85], off offset:64
	s_waitcnt vmcnt(7)
	v_lshlrev_b32_e32 v78, 16, v89
	v_and_b32_e32 v79, 0xffff0000, v89
	v_pk_mul_f32 v[78:79], v[116:117], v[78:79]
	s_waitcnt vmcnt(6)
	v_lshlrev_b32_e32 v80, 16, v90
	v_cvt_pk_bf16_f32 v87, v78, v79
	v_pk_mul_f32 v[78:79], v[40:41], v[92:93] op_sel_hi:[1,0]
	v_and_b32_e32 v81, 0xffff0000, v90
	v_pk_mul_f32 v[78:79], v[78:79], v[80:81]
	v_pk_mul_f32 v[80:81], v[42:43], v[92:93] op_sel_hi:[1,0]
	v_lshlrev_b32_e32 v82, 16, v91
	v_and_b32_e32 v83, 0xffff0000, v91
	v_pk_mul_f32 v[80:81], v[80:81], v[82:83]
	v_cvt_pk_bf16_f32 v78, v78, v79
	v_cvt_pk_bf16_f32 v79, v80, v81
	global_store_dwordx2 v[74:75], v[78:79], off offset:96
	v_pk_mul_f32 v[78:79], v[44:45], v[92:93] op_sel_hi:[1,0]
	s_waitcnt vmcnt(6)
	v_lshlrev_b32_e32 v80, 16, v76
	v_and_b32_e32 v81, 0xffff0000, v76
	v_pk_mul_f32 v[78:79], v[78:79], v[80:81]
	v_lshlrev_b32_e32 v132, 16, v88
	v_and_b32_e32 v133, 0xffff0000, v88
	v_cvt_pk_bf16_f32 v76, v78, v79
	v_pk_mul_f32 v[78:79], v[46:47], v[92:93] op_sel_hi:[1,0]
	v_lshlrev_b32_e32 v80, 16, v77
	v_and_b32_e32 v81, 0xffff0000, v77
	v_pk_mul_f32 v[104:105], v[114:115], v[132:133]
	v_pk_mul_f32 v[78:79], v[78:79], v[80:81]
	v_cvt_pk_bf16_f32 v86, v104, v105
	v_cvt_pk_bf16_f32 v77, v78, v79
	global_store_dwordx2 v[74:75], v[86:87], off offset:80
	global_store_dwordx2 v[74:75], v[76:77], off offset:112
	s_cbranch_execnz .LBB0_282

.LBB0_309:
	s_cmpk_gt_u32 s36, 0xff
	s_waitcnt lgkmcnt(0)
	s_barrier
	s_cbranch_scc1 .LBB0_244
	ds_read2st64_b32 v[80:81], v64 offset1:1
	ds_read2st64_b32 v[82:83], v64 offset0:2 offset1:3
	ds_read2st64_b32 v[84:85], v64 offset0:4 offset1:5
	ds_read2st64_b32 v[86:87], v64 offset0:6 offset1:7
	ds_read2st64_b32 v[88:89], v64 offset0:8 offset1:9
	ds_read2st64_b32 v[128:129], v64 offset0:10 offset1:11
	ds_read2st64_b32 v[132:133], v64 offset0:12 offset1:13
	ds_read2st64_b32 v[134:135], v64 offset0:14 offset1:15
	ds_read2st64_b32 v[136:137], v64 offset0:16 offset1:17
	ds_read2st64_b32 v[138:139], v64 offset0:18 offset1:19
	ds_read2st64_b32 v[140:141], v64 offset0:20 offset1:21
	ds_read2st64_b32 v[142:143], v64 offset0:22 offset1:23
	ds_read2st64_b32 v[144:145], v64 offset0:24 offset1:25
	ds_read2st64_b32 v[146:147], v64 offset0:26 offset1:27
	ds_read2st64_b32 v[126:127], v64 offset0:28 offset1:29
	ds_read2st64_b32 v[148:149], v64 offset0:30 offset1:31
	ds_read2st64_b32 v[118:119], v64 offset0:32 offset1:33
	ds_read2st64_b32 v[122:123], v64 offset0:34 offset1:35
	ds_read2st64_b32 v[108:109], v64 offset0:36 offset1:37
	ds_read2st64_b32 v[116:117], v64 offset0:38 offset1:39
	ds_read2st64_b32 v[96:97], v64 offset0:40 offset1:41
	ds_read2st64_b32 v[102:103], v64 offset0:42 offset1:43
	ds_read2st64_b32 v[94:95], v64 offset0:44 offset1:45
	ds_read2st64_b32 v[98:99], v64 offset0:46 offset1:47
	ds_read2st64_b32 v[90:91], v64 offset0:56 offset1:57
	ds_read2st64_b32 v[92:93], v64 offset0:58 offset1:59
	ds_read2st64_b32 v[66:67], v64 offset0:60 offset1:61
	ds_read2st64_b32 v[68:69], v64 offset0:62 offset1:63
	ds_read2st64_b32 v[106:107], v64 offset0:48 offset1:49
	ds_read2st64_b32 v[112:113], v64 offset0:50 offset1:51
	ds_read2st64_b32 v[100:101], v64 offset0:52 offset1:53
	ds_read2st64_b32 v[104:105], v64 offset0:54 offset1:55
	s_waitcnt lgkmcnt(14)
	v_pk_mul_f32 v[80:81], v[180:181], v[80:81]
	v_pk_mul_f32 v[82:83], v[180:181], v[82:83]
	v_pk_fma_f32 v[48:49], v[48:49], v[70:71], v[80:81] op_sel_hi:[1,0,1] neg_lo:[0,0,1] neg_hi:[0,0,1]
	v_pk_mul_f32 v[80:81], v[180:181], v[86:87]
	v_pk_fma_f32 v[50:51], v[50:51], v[70:71], v[82:83] op_sel_hi:[1,0,1] neg_lo:[0,0,1] neg_hi:[0,0,1]
	v_pk_fma_f32 v[54:55], v[54:55], v[70:71], v[80:81] op_sel_hi:[1,0,1] neg_lo:[0,0,1] neg_hi:[0,0,1]
	v_pk_mul_f32 v[80:81], v[180:181], v[84:85]
	s_lshl_b32 s4, s27, 23
	v_pk_fma_f32 v[80:81], v[52:53], v[70:71], v[80:81] op_sel_hi:[1,0,1] neg_lo:[0,0,1] neg_hi:[0,0,1]
	v_pk_mul_f32 v[52:53], v[180:181], v[128:129]
	s_lshl_b32 s5, s26, 7
	v_pk_fma_f32 v[52:53], v[58:59], v[70:71], v[52:53] op_sel_hi:[1,0,1] neg_lo:[0,0,1] neg_hi:[0,0,1]
	v_pk_mul_f32 v[58:59], v[180:181], v[88:89]
	s_add_i32 s5, s5, s4
	v_pk_fma_f32 v[82:83], v[56:57], v[70:71], v[58:59] op_sel_hi:[1,0,1] neg_lo:[0,0,1] neg_hi:[0,0,1]
	v_pk_mul_f32 v[56:57], v[180:181], v[134:135]
	v_lshl_add_u32 v130, v159, 10, s5
	v_pk_fma_f32 v[62:63], v[62:63], v[70:71], v[56:57] op_sel_hi:[1,0,1] neg_lo:[0,0,1] neg_hi:[0,0,1]
	v_pk_mul_f32 v[56:57], v[180:181], v[132:133]
	s_waitcnt lgkmcnt(5)
	v_pk_mul_f32 v[64:65], v[180:181], v[66:67]
	v_pk_fma_f32 v[86:87], v[60:61], v[70:71], v[56:57] op_sel_hi:[1,0,1] neg_lo:[0,0,1] neg_hi:[0,0,1]
	v_pk_mul_f32 v[56:57], v[180:181], v[138:139]
	v_lshlrev_b64 v[72:73], 1, v[130:131]
	v_pk_fma_f32 v[56:57], v[34:35], v[70:71], v[56:57] op_sel_hi:[1,0,1] neg_lo:[0,0,1] neg_hi:[0,0,1]
	v_pk_mul_f32 v[34:35], v[180:181], v[136:137]
	v_pk_fma_f32 v[64:65], v[12:13], v[70:71], v[64:65] op_sel_hi:[1,0,1] neg_lo:[0,0,1] neg_hi:[0,0,1]
	v_pk_fma_f32 v[60:61], v[32:33], v[70:71], v[34:35] op_sel_hi:[1,0,1] neg_lo:[0,0,1] neg_hi:[0,0,1]
	v_pk_mul_f32 v[32:33], v[180:181], v[142:143]
	s_waitcnt lgkmcnt(4)
	v_pk_mul_f32 v[12:13], v[180:181], v[68:69]
	v_pk_fma_f32 v[58:59], v[38:39], v[70:71], v[32:33] op_sel_hi:[1,0,1] neg_lo:[0,0,1] neg_hi:[0,0,1]
	v_pk_mul_f32 v[32:33], v[180:181], v[140:141]
	v_lshl_add_u64 v[68:69], s[16:17], 0, v[72:73]
	v_pk_fma_f32 v[84:85], v[36:37], v[70:71], v[32:33] op_sel_hi:[1,0,1] neg_lo:[0,0,1] neg_hi:[0,0,1]
	v_pk_mul_f32 v[32:33], v[180:181], v[146:147]
	v_mov_b32_e32 v159, v131
	v_pk_fma_f32 v[42:43], v[42:43], v[70:71], v[32:33] op_sel_hi:[1,0,1] neg_lo:[0,0,1] neg_hi:[0,0,1]
	v_pk_mul_f32 v[32:33], v[180:181], v[144:145]
	v_pk_mul_f32 v[114:115], v[48:49], v[48:49]
	v_pk_fma_f32 v[88:89], v[40:41], v[70:71], v[32:33] op_sel_hi:[1,0,1] neg_lo:[0,0,1] neg_hi:[0,0,1]
	v_pk_mul_f32 v[32:33], v[180:181], v[148:149]
	v_pk_fma_f32 v[66:67], v[14:15], v[70:71], v[12:13] op_sel_hi:[1,0,1] neg_lo:[0,0,1] neg_hi:[0,0,1]
	v_pk_fma_f32 v[40:41], v[46:47], v[70:71], v[32:33] op_sel_hi:[1,0,1] neg_lo:[0,0,1] neg_hi:[0,0,1]
	v_pk_mul_f32 v[32:33], v[180:181], v[126:127]
	global_load_dwordx4 v[12:15], v156, s[40:41]
	v_pk_fma_f32 v[44:45], v[44:45], v[70:71], v[32:33] op_sel_hi:[1,0,1] neg_lo:[0,0,1] neg_hi:[0,0,1]
	v_pk_mul_f32 v[32:33], v[180:181], v[122:123]
	v_lshl_add_u64 v[68:69], v[68:69], 0, v[158:159]
	v_pk_fma_f32 v[32:33], v[18:19], v[70:71], v[32:33] op_sel_hi:[1,0,1] neg_lo:[0,0,1] neg_hi:[0,0,1]
	v_pk_mul_f32 v[18:19], v[180:181], v[118:119]
	v_pk_mul_f32 v[110:111], v[50:51], v[50:51]
	v_pk_fma_f32 v[34:35], v[16:17], v[70:71], v[18:19] op_sel_hi:[1,0,1] neg_lo:[0,0,1] neg_hi:[0,0,1]
	v_pk_mul_f32 v[16:17], v[180:181], v[116:117]
	global_load_dwordx2 v[76:77], v[68:69], off nt
	v_pk_fma_f32 v[36:37], v[22:23], v[70:71], v[16:17] op_sel_hi:[1,0,1] neg_lo:[0,0,1] neg_hi:[0,0,1]
	v_pk_mul_f32 v[16:17], v[180:181], v[108:109]
	v_pk_mul_f32 v[124:125], v[80:81], v[80:81]
	v_pk_fma_f32 v[38:39], v[20:21], v[70:71], v[16:17] op_sel_hi:[1,0,1] neg_lo:[0,0,1] neg_hi:[0,0,1]
	v_pk_mul_f32 v[16:17], v[180:181], v[102:103]
	v_pk_mul_f32 v[120:121], v[54:55], v[54:55]
	v_pk_fma_f32 v[26:27], v[26:27], v[70:71], v[16:17] op_sel_hi:[1,0,1] neg_lo:[0,0,1] neg_hi:[0,0,1]
	v_pk_mul_f32 v[16:17], v[180:181], v[96:97]
	v_pk_mul_f32 v[150:151], v[82:83], v[82:83]
	v_pk_fma_f32 v[24:25], v[24:25], v[70:71], v[16:17] op_sel_hi:[1,0,1] neg_lo:[0,0,1] neg_hi:[0,0,1]
	v_pk_mul_f32 v[16:17], v[180:181], v[98:99]
	v_pk_mul_f32 v[128:129], v[52:53], v[52:53]
	v_pk_fma_f32 v[20:21], v[30:31], v[70:71], v[16:17] op_sel_hi:[1,0,1] neg_lo:[0,0,1] neg_hi:[0,0,1]
	v_pk_mul_f32 v[16:17], v[180:181], v[94:95]
	v_pk_mul_f32 v[132:133], v[86:87], v[86:87]
	v_pk_fma_f32 v[22:23], v[28:29], v[70:71], v[16:17] op_sel_hi:[1,0,1] neg_lo:[0,0,1] neg_hi:[0,0,1]
	s_waitcnt lgkmcnt(2)
	v_pk_mul_f32 v[16:17], v[180:181], v[112:113]
	v_pk_mul_f32 v[134:135], v[62:63], v[62:63]
	v_pk_fma_f32 v[16:17], v[2:3], v[70:71], v[16:17] op_sel_hi:[1,0,1] neg_lo:[0,0,1] neg_hi:[0,0,1]
	v_pk_mul_f32 v[2:3], v[180:181], v[106:107]
	v_pk_mul_f32 v[136:137], v[60:61], v[60:61]
	v_pk_fma_f32 v[18:19], v[0:1], v[70:71], v[2:3] op_sel_hi:[1,0,1] neg_lo:[0,0,1] neg_hi:[0,0,1]
	s_waitcnt lgkmcnt(0)
	v_pk_mul_f32 v[0:1], v[180:181], v[104:105]
	v_pk_mul_f32 v[2:3], v[180:181], v[100:101]
	v_pk_fma_f32 v[0:1], v[6:7], v[70:71], v[0:1] op_sel_hi:[1,0,1] neg_lo:[0,0,1] neg_hi:[0,0,1]
	v_pk_fma_f32 v[4:5], v[4:5], v[70:71], v[2:3] op_sel_hi:[1,0,1] neg_lo:[0,0,1] neg_hi:[0,0,1]
	v_pk_mul_f32 v[2:3], v[180:181], v[92:93]
	v_pk_mul_f32 v[6:7], v[180:181], v[90:91]
	v_pk_fma_f32 v[2:3], v[10:11], v[70:71], v[2:3] op_sel_hi:[1,0,1] neg_lo:[0,0,1] neg_hi:[0,0,1]
	v_pk_fma_f32 v[6:7], v[8:9], v[70:71], v[6:7] op_sel_hi:[1,0,1] neg_lo:[0,0,1] neg_hi:[0,0,1]
	v_add_f32_e32 v70, v114, v115
	v_add_f32_e32 v70, v70, v110
	v_add_f32_e32 v70, v70, v111
	v_add_f32_e32 v70, v70, v124
	v_add_f32_e32 v70, v70, v125
	v_add_f32_e32 v70, v70, v120
	v_add_f32_e32 v70, v70, v121
	v_add_f32_e32 v70, v70, v150
	v_add_f32_e32 v70, v70, v151
	v_add_f32_e32 v70, v70, v128
	v_add_f32_e32 v70, v70, v129
	v_add_f32_e32 v70, v70, v132
	v_add_f32_e32 v70, v70, v133
	v_add_f32_e32 v70, v70, v134
	v_add_f32_e32 v70, v70, v135
	v_add_f32_e32 v70, v70, v136
	v_pk_mul_f32 v[138:139], v[56:57], v[56:57]
	v_add_f32_e32 v70, v70, v137
	v_add_f32_e32 v70, v70, v138
	v_pk_mul_f32 v[140:141], v[84:85], v[84:85]
	v_add_f32_e32 v70, v70, v139
	v_add_f32_e32 v70, v70, v140
	v_pk_mul_f32 v[142:143], v[58:59], v[58:59]
	v_add_f32_e32 v70, v70, v141
	v_add_f32_e32 v70, v70, v142
	v_pk_mul_f32 v[144:145], v[88:89], v[88:89]
	v_add_f32_e32 v70, v70, v143
	v_add_f32_e32 v70, v70, v144
	v_pk_mul_f32 v[146:147], v[42:43], v[42:43]
	v_add_f32_e32 v70, v70, v145
	v_add_f32_e32 v70, v70, v146
	v_pk_mul_f32 v[126:127], v[44:45], v[44:45]
	v_add_f32_e32 v70, v70, v147
	v_add_f32_e32 v70, v70, v126
	v_pk_mul_f32 v[46:47], v[40:41], v[40:41]
	v_add_f32_e32 v70, v70, v127
	v_add_f32_e32 v46, v70, v46
	v_pk_mul_f32 v[118:119], v[34:35], v[34:35]
	v_add_f32_e32 v46, v46, v47
	v_add_f32_e32 v46, v46, v118
	v_pk_mul_f32 v[122:123], v[32:33], v[32:33]
	v_add_f32_e32 v46, v46, v119
	v_add_f32_e32 v46, v46, v122
	v_pk_mul_f32 v[108:109], v[38:39], v[38:39]
	v_add_f32_e32 v46, v46, v123
	v_add_f32_e32 v46, v46, v108
	v_pk_mul_f32 v[116:117], v[36:37], v[36:37]
	v_add_f32_e32 v46, v46, v109
	v_add_f32_e32 v46, v46, v116
	v_pk_mul_f32 v[96:97], v[24:25], v[24:25]
	v_add_f32_e32 v46, v46, v117
	v_add_f32_e32 v46, v46, v96
	v_pk_mul_f32 v[102:103], v[26:27], v[26:27]
	v_add_f32_e32 v46, v46, v97
	v_add_f32_e32 v46, v46, v102
	v_pk_mul_f32 v[28:29], v[22:23], v[22:23]
	v_add_f32_e32 v46, v46, v103
	v_add_f32_e32 v28, v46, v28
	v_pk_mul_f32 v[30:31], v[20:21], v[20:21]
	v_add_f32_e32 v28, v28, v29
	v_add_f32_e32 v28, v28, v30
	v_pk_mul_f32 v[98:99], v[18:19], v[18:19]
	v_add_f32_e32 v28, v28, v31
	v_add_f32_e32 v28, v28, v98
	v_pk_mul_f32 v[94:95], v[16:17], v[16:17]
	v_add_f32_e32 v28, v28, v99
	v_add_f32_e32 v28, v28, v94
	v_pk_mul_f32 v[100:101], v[4:5], v[4:5]
	v_add_f32_e32 v28, v28, v95
	v_add_f32_e32 v28, v28, v100
	v_pk_mul_f32 v[104:105], v[0:1], v[0:1]
	v_add_f32_e32 v28, v28, v101
	v_add_f32_e32 v28, v28, v104
	v_pk_mul_f32 v[8:9], v[6:7], v[6:7]
	v_add_f32_e32 v28, v28, v105
	v_add_f32_e32 v8, v28, v8
	v_pk_mul_f32 v[10:11], v[2:3], v[2:3]
	v_add_f32_e32 v8, v8, v9
	v_add_f32_e32 v8, v8, v10
	v_pk_mul_f32 v[74:75], v[64:65], v[64:65]
	v_add_f32_e32 v8, v8, v11
	v_add_f32_e32 v8, v8, v74
	v_pk_mul_f32 v[78:79], v[66:67], v[66:67]
	v_add_f32_e32 v8, v8, v75
	v_add_f32_e32 v8, v8, v78
	v_add_f32_e32 v8, v8, v79
	ds_bpermute_b32 v9, v194, v8
	s_waitcnt vmcnt(0)
	v_lshlrev_b32_e32 v70, 16, v76
	v_and_b32_e32 v71, 0xffff0000, v76
	v_lshlrev_b32_e32 v74, 16, v77
	v_and_b32_e32 v75, 0xffff0000, v77
	s_waitcnt lgkmcnt(0)
	v_add_f32_e32 v8, v8, v9
	v_fmamk_f32 v8, v8, 0x3c000000, v195
	v_mul_f32_e32 v9, 0x4b800000, v8
	v_cmp_gt_f32_e32 vcc, s65, v8
	global_load_dwordx2 v[28:29], v[68:69], off offset:16 nt
	global_load_dwordx2 v[30:31], v[68:69], off offset:32 nt
	global_load_dwordx2 v[46:47], v[68:69], off offset:48 nt
	v_cndmask_b32_e32 v8, v8, v9, vcc
	v_rsq_f32_e32 v10, v8
	v_lshl_add_u64 v[8:9], s[18:19], 0, v[72:73]
	v_lshl_add_u64 v[8:9], v[8:9], 0, v[158:159]
	v_mul_f32_e32 v11, 0x45800000, v10
	v_cndmask_b32_e32 v10, v10, v11, vcc
	v_mul_f32_e32 v10, 0x3f4ccccd, v10
	v_pk_mul_f32 v[48:49], v[48:49], v[10:11] op_sel_hi:[1,0]
	v_pk_mul_f32 v[42:43], v[42:43], v[10:11] op_sel_hi:[1,0]
	v_pk_mul_f32 v[12:13], v[12:13], v[48:49]
	v_pk_mul_f32 v[48:49], v[50:51], v[10:11] op_sel_hi:[1,0]
	v_pk_mul_f32 v[12:13], v[12:13], v[70:71]
	v_pk_mul_f32 v[14:15], v[14:15], v[48:49]
	v_cvt_pk_bf16_f32 v12, v12, v13
	v_pk_mul_f32 v[14:15], v[14:15], v[74:75]
	v_pk_mul_f32 v[50:51], v[80:81], v[10:11] op_sel_hi:[1,0]
	v_cvt_pk_bf16_f32 v13, v14, v15
	global_store_dwordx2 v[8:9], v[12:13], off
	global_load_dwordx4 v[12:15], v156, s[40:41] offset:32
	v_pk_mul_f32 v[44:45], v[44:45], v[10:11] op_sel_hi:[1,0]
	v_pk_mul_f32 v[40:41], v[40:41], v[10:11] op_sel_hi:[1,0]
	v_pk_mul_f32 v[34:35], v[34:35], v[10:11] op_sel_hi:[1,0]
	v_pk_mul_f32 v[32:33], v[32:33], v[10:11] op_sel_hi:[1,0]
	v_pk_mul_f32 v[24:25], v[24:25], v[10:11] op_sel_hi:[1,0]
	v_pk_mul_f32 v[26:27], v[26:27], v[10:11] op_sel_hi:[1,0]
	v_pk_mul_f32 v[22:23], v[22:23], v[10:11] op_sel_hi:[1,0]
	v_pk_mul_f32 v[20:21], v[20:21], v[10:11] op_sel_hi:[1,0]
	v_pk_mul_f32 v[18:19], v[18:19], v[10:11] op_sel_hi:[1,0]
	v_pk_mul_f32 v[16:17], v[16:17], v[10:11] op_sel_hi:[1,0]
	v_pk_mul_f32 v[4:5], v[4:5], v[10:11] op_sel_hi:[1,0]
	v_pk_mul_f32 v[0:1], v[0:1], v[10:11] op_sel_hi:[1,0]
	v_pk_mul_f32 v[6:7], v[6:7], v[10:11] op_sel_hi:[1,0]
	v_pk_mul_f32 v[2:3], v[2:3], v[10:11] op_sel_hi:[1,0]
	s_waitcnt vmcnt(4)
	v_lshlrev_b32_e32 v48, 16, v28
	v_and_b32_e32 v49, 0xffff0000, v28
	v_lshlrev_b32_e32 v28, 16, v29
	v_and_b32_e32 v29, 0xffff0000, v29
	s_waitcnt vmcnt(0)
	v_pk_mul_f32 v[12:13], v[12:13], v[50:51]
	s_nop 0
	v_pk_mul_f32 v[12:13], v[12:13], v[48:49]
	v_pk_mul_f32 v[48:49], v[54:55], v[10:11] op_sel_hi:[1,0]
	v_cvt_pk_bf16_f32 v12, v12, v13
	v_pk_mul_f32 v[14:15], v[14:15], v[48:49]
	v_pk_mul_f32 v[48:49], v[82:83], v[10:11] op_sel_hi:[1,0]
	v_pk_mul_f32 v[14:15], v[14:15], v[28:29]
	v_pk_mul_f32 v[50:51], v[52:53], v[10:11] op_sel_hi:[1,0]
	v_cvt_pk_bf16_f32 v13, v14, v15
	global_store_dwordx2 v[8:9], v[12:13], off offset:16
	global_load_dwordx4 v[12:15], v156, s[40:41] offset:64
	v_lshlrev_b32_e32 v28, 16, v30
	v_and_b32_e32 v29, 0xffff0000, v30
	v_lshlrev_b32_e32 v30, 16, v31
	v_and_b32_e32 v31, 0xffff0000, v31
	v_pk_mul_f32 v[52:53], v[60:61], v[10:11] op_sel_hi:[1,0]
	v_pk_mul_f32 v[54:55], v[56:57], v[10:11] op_sel_hi:[1,0]
	s_waitcnt vmcnt(0)
	v_pk_mul_f32 v[12:13], v[48:49], v[12:13]
	v_pk_mul_f32 v[14:15], v[50:51], v[14:15]
	v_pk_mul_f32 v[12:13], v[12:13], v[28:29]
	v_pk_mul_f32 v[14:15], v[14:15], v[30:31]
	v_cvt_pk_bf16_f32 v12, v12, v13
	v_cvt_pk_bf16_f32 v13, v14, v15
	global_store_dwordx2 v[8:9], v[12:13], off offset:32
	global_load_dwordx4 v[12:15], v156, s[40:41] offset:96
	s_nop 0
	global_load_dwordx2 v[28:29], v[68:69], off offset:64 nt
	v_pk_mul_f32 v[48:49], v[86:87], v[10:11] op_sel_hi:[1,0]
	v_pk_mul_f32 v[50:51], v[62:63], v[10:11] op_sel_hi:[1,0]
	v_lshlrev_b32_e32 v30, 16, v46
	v_and_b32_e32 v31, 0xffff0000, v46
	v_lshlrev_b32_e32 v46, 16, v47
	v_and_b32_e32 v47, 0xffff0000, v47
	s_waitcnt vmcnt(1)
	v_pk_mul_f32 v[12:13], v[48:49], v[12:13]
	v_pk_mul_f32 v[14:15], v[50:51], v[14:15]
	v_pk_mul_f32 v[12:13], v[12:13], v[30:31]
	v_pk_mul_f32 v[14:15], v[14:15], v[46:47]
	v_cvt_pk_bf16_f32 v12, v12, v13
	v_cvt_pk_bf16_f32 v13, v14, v15
	global_store_dwordx2 v[8:9], v[12:13], off offset:48
	global_load_dwordx4 v[12:15], v156, s[40:41] offset:128
	s_nop 0
	global_load_dwordx2 v[30:31], v[68:69], off offset:80 nt
	global_load_dwordx2 v[46:47], v[68:69], off offset:96 nt
	global_load_dwordx2 v[48:49], v[68:69], off offset:112 nt
	s_waitcnt vmcnt(5)
	v_lshlrev_b32_e32 v50, 16, v28
	v_and_b32_e32 v51, 0xffff0000, v28
	v_lshlrev_b32_e32 v28, 16, v29
	v_and_b32_e32 v29, 0xffff0000, v29
	s_waitcnt vmcnt(3)
	v_pk_mul_f32 v[12:13], v[52:53], v[12:13]
	v_pk_mul_f32 v[14:15], v[54:55], v[14:15]
	v_pk_mul_f32 v[12:13], v[12:13], v[50:51]
	v_pk_mul_f32 v[14:15], v[14:15], v[28:29]
	v_cvt_pk_bf16_f32 v12, v12, v13
	v_cvt_pk_bf16_f32 v13, v14, v15
	global_store_dwordx2 v[8:9], v[12:13], off offset:64
	global_load_dwordx4 v[12:15], v156, s[40:41] offset:160
	v_pk_mul_f32 v[50:51], v[84:85], v[10:11] op_sel_hi:[1,0]
	v_pk_mul_f32 v[52:53], v[58:59], v[10:11] op_sel_hi:[1,0]
	s_waitcnt vmcnt(4)
	v_lshlrev_b32_e32 v28, 16, v30
	v_and_b32_e32 v29, 0xffff0000, v30
	v_lshlrev_b32_e32 v30, 16, v31
	v_and_b32_e32 v31, 0xffff0000, v31
	s_waitcnt vmcnt(0)
	v_pk_mul_f32 v[12:13], v[50:51], v[12:13]
	v_pk_mul_f32 v[14:15], v[52:53], v[14:15]
	v_pk_mul_f32 v[12:13], v[12:13], v[28:29]
	v_pk_mul_f32 v[14:15], v[14:15], v[30:31]
	v_cvt_pk_bf16_f32 v12, v12, v13
	v_cvt_pk_bf16_f32 v13, v14, v15
	global_store_dwordx2 v[8:9], v[12:13], off offset:80
	global_load_dwordx4 v[12:15], v156, s[40:41] offset:192
	v_lshlrev_b32_e32 v28, 16, v46
	v_and_b32_e32 v29, 0xffff0000, v46
	v_lshlrev_b32_e32 v30, 16, v47
	v_and_b32_e32 v31, 0xffff0000, v47
	v_pk_mul_f32 v[46:47], v[88:89], v[10:11] op_sel_hi:[1,0]
	s_waitcnt vmcnt(0)
	v_pk_mul_f32 v[14:15], v[42:43], v[14:15]
	v_pk_mul_f32 v[12:13], v[46:47], v[12:13]
	v_pk_mul_f32 v[14:15], v[14:15], v[30:31]
	v_pk_mul_f32 v[12:13], v[12:13], v[28:29]
	v_lshlrev_b32_e32 v30, 16, v48
	v_cvt_pk_bf16_f32 v12, v12, v13
	v_cvt_pk_bf16_f32 v13, v14, v15
	global_store_dwordx2 v[8:9], v[12:13], off offset:96
	global_load_dwordx4 v[12:15], v156, s[40:41] offset:224
	s_nop 0
	global_load_dwordx2 v[28:29], v[68:69], off offset:128 nt
	v_and_b32_e32 v31, 0xffff0000, v48
	v_lshlrev_b32_e32 v42, 16, v49
	v_and_b32_e32 v43, 0xffff0000, v49
	s_waitcnt vmcnt(1)
	v_pk_mul_f32 v[12:13], v[44:45], v[12:13]
	v_pk_mul_f32 v[14:15], v[40:41], v[14:15]
	v_pk_mul_f32 v[12:13], v[12:13], v[30:31]
	v_pk_mul_f32 v[14:15], v[14:15], v[42:43]
	v_cvt_pk_bf16_f32 v12, v12, v13
	v_cvt_pk_bf16_f32 v13, v14, v15
	global_store_dwordx2 v[8:9], v[12:13], off offset:112
	global_load_dwordx4 v[12:15], v156, s[40:41] offset:256
	s_nop 0
	global_load_dwordx2 v[30:31], v[68:69], off offset:144 nt
	global_load_dwordx2 v[40:41], v[68:69], off offset:160 nt
	global_load_dwordx2 v[42:43], v[68:69], off offset:176 nt
	s_waitcnt vmcnt(5)
	v_lshlrev_b32_e32 v44, 16, v28
	v_and_b32_e32 v45, 0xffff0000, v28
	v_lshlrev_b32_e32 v28, 16, v29
	v_and_b32_e32 v29, 0xffff0000, v29
	s_waitcnt vmcnt(3)
	v_pk_mul_f32 v[12:13], v[34:35], v[12:13]
	v_pk_mul_f32 v[14:15], v[32:33], v[14:15]
	v_pk_mul_f32 v[12:13], v[12:13], v[44:45]
	v_pk_mul_f32 v[14:15], v[14:15], v[28:29]
	v_cvt_pk_bf16_f32 v12, v12, v13
	v_cvt_pk_bf16_f32 v13, v14, v15
	global_store_dwordx2 v[8:9], v[12:13], off offset:128
	global_load_dwordx4 v[12:15], v156, s[40:41] offset:288
	v_pk_mul_f32 v[32:33], v[38:39], v[10:11] op_sel_hi:[1,0]
	v_pk_mul_f32 v[34:35], v[36:37], v[10:11] op_sel_hi:[1,0]
	s_waitcnt vmcnt(4)
	v_lshlrev_b32_e32 v28, 16, v30
	v_and_b32_e32 v29, 0xffff0000, v30
	v_lshlrev_b32_e32 v30, 16, v31
	v_and_b32_e32 v31, 0xffff0000, v31
	s_waitcnt vmcnt(0)
	v_pk_mul_f32 v[12:13], v[32:33], v[12:13]
	v_pk_mul_f32 v[14:15], v[34:35], v[14:15]
	v_pk_mul_f32 v[12:13], v[12:13], v[28:29]
	v_pk_mul_f32 v[14:15], v[14:15], v[30:31]
	v_cvt_pk_bf16_f32 v12, v12, v13
	v_cvt_pk_bf16_f32 v13, v14, v15
	global_store_dwordx2 v[8:9], v[12:13], off offset:144
	global_load_dwordx4 v[12:15], v156, s[40:41] offset:320
	v_lshlrev_b32_e32 v28, 16, v40
	v_and_b32_e32 v29, 0xffff0000, v40
	v_lshlrev_b32_e32 v30, 16, v41
	v_and_b32_e32 v31, 0xffff0000, v41
	s_waitcnt vmcnt(0)
	v_pk_mul_f32 v[12:13], v[24:25], v[12:13]
	v_pk_mul_f32 v[14:15], v[26:27], v[14:15]
	v_pk_mul_f32 v[12:13], v[12:13], v[28:29]
	v_pk_mul_f32 v[14:15], v[14:15], v[30:31]
	v_cvt_pk_bf16_f32 v12, v12, v13
	v_cvt_pk_bf16_f32 v13, v14, v15
	global_store_dwordx2 v[8:9], v[12:13], off offset:160
	global_load_dwordx4 v[12:15], v156, s[40:41] offset:352
	s_nop 0
	global_load_dwordx2 v[24:25], v[68:69], off offset:192 nt
	v_lshlrev_b32_e32 v26, 16, v42
	v_and_b32_e32 v27, 0xffff0000, v42
	v_lshlrev_b32_e32 v28, 16, v43
	v_and_b32_e32 v29, 0xffff0000, v43
	s_waitcnt vmcnt(1)
	v_pk_mul_f32 v[12:13], v[22:23], v[12:13]
	v_pk_mul_f32 v[14:15], v[20:21], v[14:15]
	v_pk_mul_f32 v[12:13], v[12:13], v[26:27]
	v_pk_mul_f32 v[14:15], v[14:15], v[28:29]
	v_cvt_pk_bf16_f32 v12, v12, v13
	v_cvt_pk_bf16_f32 v13, v14, v15
	global_store_dwordx2 v[8:9], v[12:13], off offset:176
	global_load_dwordx4 v[12:15], v156, s[40:41] offset:384
	s_nop 0
	global_load_dwordx2 v[20:21], v[68:69], off offset:208 nt
	global_load_dwordx2 v[22:23], v[68:69], off offset:224 nt
	global_load_dwordx2 v[26:27], v[68:69], off offset:240 nt
	s_waitcnt vmcnt(5)
	v_lshlrev_b32_e32 v28, 16, v24
	v_and_b32_e32 v29, 0xffff0000, v24
	v_lshlrev_b32_e32 v24, 16, v25
	v_and_b32_e32 v25, 0xffff0000, v25
	s_waitcnt vmcnt(3)
	v_pk_mul_f32 v[12:13], v[18:19], v[12:13]
	v_pk_mul_f32 v[14:15], v[16:17], v[14:15]
	v_pk_mul_f32 v[12:13], v[12:13], v[28:29]
	v_pk_mul_f32 v[14:15], v[14:15], v[24:25]
	v_cvt_pk_bf16_f32 v12, v12, v13
	v_cvt_pk_bf16_f32 v13, v14, v15
	global_store_dwordx2 v[8:9], v[12:13], off offset:192
	global_load_dwordx4 v[12:15], v156, s[40:41] offset:416
	s_waitcnt vmcnt(4)
	v_lshlrev_b32_e32 v16, 16, v20
	v_and_b32_e32 v17, 0xffff0000, v20
	v_lshlrev_b32_e32 v18, 16, v21
	v_and_b32_e32 v19, 0xffff0000, v21
	s_waitcnt vmcnt(0)
	v_pk_mul_f32 v[4:5], v[4:5], v[12:13]
	v_pk_mul_f32 v[0:1], v[0:1], v[14:15]
	v_pk_mul_f32 v[4:5], v[4:5], v[16:17]
	v_pk_mul_f32 v[0:1], v[0:1], v[18:19]
	v_cvt_pk_bf16_f32 v4, v4, v5
	v_cvt_pk_bf16_f32 v5, v0, v1
	global_store_dwordx2 v[8:9], v[4:5], off offset:208
	global_load_dwordx4 v[12:15], v156, s[40:41] offset:448
	v_lshlrev_b32_e32 v0, 16, v22
	v_and_b32_e32 v1, 0xffff0000, v22
	v_lshlrev_b32_e32 v4, 16, v23
	v_and_b32_e32 v5, 0xffff0000, v23
	s_waitcnt vmcnt(0)
	v_pk_mul_f32 v[6:7], v[6:7], v[12:13]
	v_pk_mul_f32 v[2:3], v[2:3], v[14:15]
	v_pk_mul_f32 v[0:1], v[6:7], v[0:1]
	v_pk_mul_f32 v[2:3], v[2:3], v[4:5]
	v_cvt_pk_bf16_f32 v0, v0, v1
	v_cvt_pk_bf16_f32 v1, v2, v3
	global_store_dwordx2 v[8:9], v[0:1], off offset:224
	global_load_dwordx4 v[0:3], v156, s[40:41] offset:480
	v_pk_mul_f32 v[12:13], v[64:65], v[10:11] op_sel_hi:[1,0]
	v_pk_mul_f32 v[10:11], v[66:67], v[10:11] op_sel_hi:[1,0]
	v_lshlrev_b32_e32 v4, 16, v26
	v_and_b32_e32 v5, 0xffff0000, v26
	v_lshlrev_b32_e32 v6, 16, v27
	v_and_b32_e32 v7, 0xffff0000, v27
	s_waitcnt vmcnt(0)
	v_pk_mul_f32 v[0:1], v[12:13], v[0:1]
	v_pk_mul_f32 v[2:3], v[10:11], v[2:3]
	v_pk_mul_f32 v[0:1], v[0:1], v[4:5]
	v_pk_mul_f32 v[2:3], v[2:3], v[6:7]
	v_cvt_pk_bf16_f32 v0, v0, v1
	v_cvt_pk_bf16_f32 v1, v2, v3
	global_store_dwordx2 v[8:9], v[0:1], off offset:240
	s_branch .LBB0_244
